# phase-0 transpose items remapped so the extra early/late items fall on workgroups with no / lighter adaLN load
# baseline (speedup 1.0000x reference)
.LBB0_34:
	s_mov_b32 s0, s74
	v_ashrrev_i32_e32 v3, 6, v2
	s_lshl_b32 s24, s78, 3
	v_lshl_add_u32 v1, s0, 3, v3
	v_add_u32_e32 v1, 0x200, v1
	v_subrev_u32_e32 v4, s24, v1
	v_cmp_le_u32_e32 vcc, s24, v1
	s_nop 1
	v_cndmask_b32_e32 v1, v1, v4, vcc
	s_movk_i32 s0, 0x980
	v_cmp_gt_i32_e32 vcc, s0, v1
	s_and_saveexec_b64 s[0:1], vcc
	s_cbranch_execz .LBB0_75
	s_movk_i32 s2, 0x2100
	v_and_b32_e32 v24, 31, v2
	v_bfe_u32 v25, v2, 5, 1
	v_bfe_u32 v26, v2, 3, 3
	v_lshlrev_b32_e32 v2, 3, v2
	v_mul_lo_u32 v6, v3, s2
	v_and_b32_e32 v2, 56, v2
	v_add_u32_e32 v3, 0, v6
	v_mul_u32_u24_e32 v4, 0x84, v2
	v_lshlrev_b32_e32 v5, 2, v26
	v_readlane_b32 s8, v253, 2
	v_add3_u32 v27, v3, v4, v5
	v_lshlrev_b32_e32 v2, 1, v2
	v_mov_b32_e32 v3, 0
	v_readlane_b32 s9, v253, 3
	s_mov_b64 s[2:3], 0xb00000
	v_or_b32_e32 v28, 8, v26
	v_lshl_add_u64 v[4:5], s[8:9], 0, v[2:3]
	v_mul_u32_u24_e32 v2, 0x84, v25
	v_or_b32_e32 v2, v6, v2
	v_lshlrev_b32_e32 v6, 2, v24
	v_or_b32_e32 v29, 16, v26
	v_or_b32_e32 v30, 24, v26
	v_lshl_add_u64 v[4:5], v[4:5], 0, s[2:3]
	v_add3_u32 v31, v2, v6, 0
	v_or_b32_e32 v32, 14, v25
	v_or_b32_e32 v33, 12, v25
	v_or_b32_e32 v34, 10, v25
	v_or_b32_e32 v35, 8, v25
	v_or_b32_e32 v36, 6, v25
	v_or_b32_e32 v37, 4, v25
	v_or_b32_e32 v38, 2, v25
	s_mov_b64 s[2:3], 0
	s_mov_b32 s18, 0x6bca1af3
	s_movk_i32 s19, 0x98
	s_movk_i32 s20, 0x7ff
	s_movk_i32 s21, 0x97f
	s_movk_i32 s22, 0x99f
	s_movk_i32 s23, 0x9af
	s_movk_i32 s25, 0x9ff
	s_movk_i32 s26, 0xaff
	s_movk_i32 s27, 0x4ac0
	v_readlane_b32 s10, v253, 4
	v_readlane_b32 s11, v253, 5
	s_branch .LBB0_37

.LBB0_75:
	s_or_b64 exec, exec, s[0:1]
	v_mov_b32_e32 v1, v202
	s_mov_b32 s0, s74
	s_barrier
	s_nop 0
	v_ashrrev_i32_e32 v2, 6, v1
	v_lshl_add_u32 v3, s0, 3, v2
	v_sub_u32_e32 v3, s24, v3
	v_add_u32_e32 v3, -1, v3
	s_movk_i32 s0, 0x1510
	v_cmp_gt_i32_e32 vcc, s0, v3
	s_and_saveexec_b64 s[0:1], vcc
	s_cbranch_execz .LBB0_170
	s_movk_i32 s2, 0x2100
	v_add_u32_e32 v5, 0x980, v3
	v_mul_lo_u32 v3, v2, s2
	v_and_b32_e32 v46, 31, v1
	v_bfe_u32 v2, v1, 5, 1
	v_bfe_u32 v47, v1, 3, 3
	v_lshlrev_b32_e32 v1, 3, v1
	v_and_b32_e32 v1, 56, v1
	v_readlane_b32 s8, v253, 2
	v_lshlrev_b32_e32 v6, 1, v1
	v_mov_b32_e32 v7, 0
	v_readlane_b32 s9, v253, 3
	s_mov_b64 s[2:3], 0x2080000
	v_add_u32_e32 v10, 0, v3
	v_lshl_add_u64 v[26:27], s[8:9], 0, v[6:7]
	v_lshlrev_b32_e32 v28, 2, v46
	v_mul_u32_u24_e32 v11, 0x84, v1
	v_lshl_add_u64 v[8:9], v[26:27], 0, s[2:3]
	v_lshlrev_b32_e32 v1, 2, v47
	s_mov_b64 s[2:3], 0x1c80000
	v_add_u32_e32 v4, v10, v28
	v_add3_u32 v48, v10, v11, v1
	v_lshl_add_u64 v[10:11], v[26:27], 0, s[2:3]
	s_mov_b64 s[2:3], 0x1480000
	v_lshl_add_u64 v[12:13], v[26:27], 0, s[2:3]
	s_mov_b64 s[2:3], 0x2480000
	v_lshl_add_u64 v[14:15], v[26:27], 0, s[2:3]
	s_mov_b64 s[2:3], 0x2780000
	v_lshl_add_u64 v[16:17], v[26:27], 0, s[2:3]
	s_mov_b64 s[2:3], 0x2680000
	v_lshl_add_u64 v[18:19], v[26:27], 0, s[2:3]
	s_mov_b64 s[2:3], 0x2950000
	v_lshl_add_u64 v[20:21], v[26:27], 0, s[2:3]
	s_mov_b64 s[2:3], 0x2910000
	v_lshl_add_u64 v[22:23], v[26:27], 0, s[2:3]
	s_mov_b64 s[2:3], 0x2880000
	v_lshl_add_u64 v[24:25], v[26:27], 0, s[2:3]
	s_mov_b64 s[2:3], 0xb00000
	v_mul_u32_u24_e32 v6, 0x84, v2
	v_lshl_add_u64 v[26:27], v[26:27], 0, s[2:3]
	s_add_u32 s2, s92, 0x800000
	v_or_b32_e32 v3, v3, v6
	s_movk_i32 s25, 0x84
	v_or_b32_e32 v49, 8, v47
	v_or_b32_e32 v50, 16, v47
	v_or_b32_e32 v51, 24, v47
	s_addc_u32 s3, s93, 0
	v_or_b32_e32 v52, 64, v46
	v_mov_b32_e32 v1, v2
	v_add3_u32 v53, v3, v28, 0
	v_or_b32_e32 v54, 14, v2
	v_or_b32_e32 v55, 12, v2
	v_or_b32_e32 v56, 10, v2
	v_or_b32_e32 v57, 8, v2
	v_or_b32_e32 v58, 6, v2
	v_or_b32_e32 v59, 4, v2
	v_or_b32_e32 v60, 2, v2
	s_mov_b64 s[4:5], 0
	s_movk_i32 s36, 0x97f
	s_movk_i32 s37, 0xc00
	s_movk_i32 s38, 0x4ac0
	v_mov_b32_e32 v61, 0x2c0
	v_mov_b32_e32 v62, 0x3c0
	v_mov_b32_e32 v63, 0xffffff80
	v_mov_b32_e32 v64, 5
	v_readlane_b32 s10, v253, 4
	v_readlane_b32 s11, v253, 5
	s_branch .LBB0_79
